# GEMM K-loop heads aligned to 256B; ffn_up conv+silu epilogue processes 2 rows per iteration with interleaved chains; cmp_attn tile loads de-serialized
# speedup vs baseline: 1.0589x; 1.0222x over previous
.Lg1_pre:
	s_mov_b64 vcc, exec
	s_nop 1
	v_readfirstlane_b32 s100, v194
	v_readfirstlane_b32 s101, v195
	v_readfirstlane_b32 s28, v202
	v_readfirstlane_b32 s29, v203
	s_nop 3
	s_sub_u32 s28, s28, 0x100000
	s_subb_u32 s29, s29, 0
	s_nop 1
	v_subrev_u32_e32 v202, s28, v202
	v_add_u32_e32 v202, v202, v178
	v_subrev_u32_e32 v203, s28, v200
	v_add_u32_e32 v203, v203, v178
	v_subrev_u32_e32 v210, s28, v198
	v_add_u32_e32 v210, v210, v178
	v_subrev_u32_e32 v232, s28, v196
	v_add_u32_e32 v232, v232, v178
	v_subrev_u32_e32 v233, s100, v194
	v_add_u32_e32 v233, v233, v178
	v_add_u32_e32 v236, v206, v204
	v_add_u32_e32 v237, v222, v204
	v_add_u32_e32 v238, v224, v204
	v_add_u32_e32 v239, v1, v204
	s_branch .Lg1_head
	.p2align 8

.Lg2_pre:
	s_mov_b64 vcc, exec
	s_nop 1
	v_readfirstlane_b32 s100, v194
	v_readfirstlane_b32 s101, v195
	v_readfirstlane_b32 s4, v202
	v_readfirstlane_b32 s5, v203
	s_nop 3
	s_sub_u32 s4, s4, 0x100000
	s_subb_u32 s5, s5, 0
	s_nop 1
	v_subrev_u32_e32 v202, s4, v202
	v_add_u32_e32 v202, v202, v178
	v_subrev_u32_e32 v203, s4, v200
	v_add_u32_e32 v203, v203, v178
	v_subrev_u32_e32 v210, s4, v198
	v_add_u32_e32 v210, v210, v178
	v_subrev_u32_e32 v232, s4, v196
	v_add_u32_e32 v232, v232, v178
	v_subrev_u32_e32 v233, s100, v194
	v_add_u32_e32 v233, v233, v178
	v_add_u32_e32 v236, v206, v204
	v_add_u32_e32 v237, v222, v204
	v_add_u32_e32 v238, v224, v204
	v_add_u32_e32 v239, v1, v204
	s_branch .Lg2_head
	.p2align 8

.LBB0_1388:
	v_lshl_add_u64 v[6:7], v[174:175], 0, s[84:85]
	s_mov_b32 s20, 0x12fe8000
	v_add_co_u32_e32 v2, vcc, s20, v6
	s_waitcnt lgkmcnt(0)
	s_nop 0
	v_addc_co_u32_e32 v3, vcc, 0, v7, vcc
	s_barrier
	global_load_dwordx4 v[80:83], v[2:3], off offset:2048
	s_cmpk_gt_i32 s30, 0xff7f
	s_mov_b32 s20, 0x12fe9000
	v_add_co_u32_e32 v2, vcc, s20, v6
	s_nop 1
	v_addc_co_u32_e32 v3, vcc, 0, v7, vcc
	global_load_dwordx4 v[84:87], v[2:3], off offset:2048
	s_mov_b32 s20, 0x12fea000
	v_add_co_u32_e32 v2, vcc, s20, v6
	s_nop 1
	v_addc_co_u32_e32 v3, vcc, 0, v7, vcc
	global_load_dwordx4 v[88:91], v[2:3], off offset:2048
	s_mov_b32 s20, 0x12feb000
	v_add_co_u32_e32 v2, vcc, s20, v6
	s_nop 1
	v_addc_co_u32_e32 v3, vcc, 0, v7, vcc
	global_load_dwordx4 v[92:95], v[2:3], off offset:2048
	s_cselect_b64 s[20:21], -1, 0
	v_lshl_add_u64 v[2:3], v[166:167], 0, s[84:85]
	global_load_dwordx4 v[96:99], v[2:3], off
	v_lshl_add_u64 v[2:3], v[168:169], 0, s[84:85]
	global_load_dwordx4 v[100:103], v[2:3], off
	v_lshl_add_u64 v[2:3], v[170:171], 0, s[84:85]
	global_load_dwordx4 v[104:107], v[2:3], off
	v_lshl_add_u64 v[2:3], v[172:173], 0, s[84:85]
	global_load_dwordx4 v[108:111], v[2:3], off
	s_waitcnt vmcnt(7)
	ds_write_b128 v207, v[80:83]
	s_waitcnt vmcnt(6)
	ds_write_b128 v207, v[84:87] offset:4352
	s_waitcnt vmcnt(5)
	ds_write_b128 v207, v[88:91] offset:8704
	s_waitcnt vmcnt(4)
	ds_write_b128 v207, v[92:95] offset:13056
	s_waitcnt vmcnt(3)
	ds_write2_b64 v222, v[96:97], v[98:99] offset1:1
	s_waitcnt vmcnt(2)
	ds_write2_b64 v223, v[100:101], v[102:103] offset1:1
	s_waitcnt vmcnt(1)
	ds_write2_b64 v224, v[104:105], v[106:107] offset1:1
	s_waitcnt vmcnt(0)
	ds_write2_b64 v225, v[108:109], v[110:111] offset1:1
	s_waitcnt lgkmcnt(0)
	s_barrier
	s_setprio 1
	ds_read_b128 v[2:5], v226
	s_waitcnt lgkmcnt(0)
	v_mfma_f32_32x32x16_bf16 v[80:95], v[2:5], v[112:115], 0
	ds_read_b128 v[2:5], v226 offset:32
	s_waitcnt lgkmcnt(0)
	v_mfma_f32_32x32x16_bf16 v[80:95], v[2:5], v[116:119], v[80:95]
	ds_read_b128 v[2:5], v226 offset:64
	s_waitcnt lgkmcnt(0)
	v_mfma_f32_32x32x16_bf16 v[80:95], v[2:5], v[120:123], v[80:95]
	ds_read_b128 v[2:5], v226 offset:96
	s_waitcnt lgkmcnt(0)
	v_mfma_f32_32x32x16_bf16 v[80:95], v[2:5], v[124:127], v[80:95]
	ds_read_b128 v[2:5], v226 offset:128
	s_waitcnt lgkmcnt(0)
	v_mfma_f32_32x32x16_bf16 v[80:95], v[2:5], v[128:131], v[80:95]
	ds_read_b128 v[2:5], v226 offset:160
	s_waitcnt lgkmcnt(0)
	v_mfma_f32_32x32x16_bf16 v[80:95], v[2:5], v[132:135], v[80:95]
	ds_read_b128 v[2:5], v226 offset:192
	s_waitcnt lgkmcnt(0)
	v_mfma_f32_32x32x16_bf16 v[80:95], v[2:5], v[136:139], v[80:95]
	ds_read_b128 v[2:5], v226 offset:224
	s_waitcnt lgkmcnt(0)
	v_mfma_f32_32x32x16_bf16 v[80:95], v[2:5], v[140:143], v[80:95]
	s_setprio 0
	s_add_i32 s22, s31, 0x200
	s_cmpk_lt_i32 s22, 0x80
	s_cselect_b64 s[22:23], -1, 0
	v_cndmask_b32_e64 v2, 0, 1, s[20:21]
	s_mov_b64 s[26:27], -1
	s_and_b64 vcc, exec, s[22:23]
	v_add_u32_e32 v1, s31, v206
	v_cmp_ne_u32_e64 s[20:21], 1, v2
	s_cbranch_vccz .LBB0_1407
	v_add_u32_e32 v2, 0x3f0, v1
	s_and_b64 vcc, exec, s[20:21]
	v_mov_b32_e32 v3, v165
	s_cbranch_vccz .LBB0_1442
	s_and_b64 vcc, exec, s[20:21]
	v_mov_b32_e32 v4, v165
	s_cbranch_vccz .LBB0_1443

.LBB0_1474:
	v_lshl_add_u64 v[2:3], v[38:39], 0, v[150:151]
	s_barrier
	global_load_dwordx4 v[2:5], v[2:3], off
	s_cmpk_lt_i32 s29, 0x80
	s_cselect_b64 s[22:23], -1, 0
	s_cmpk_gt_i32 s29, 0x7f
	v_lshl_add_u64 v[6:7], v[36:37], 0, v[150:151]
	global_load_dwordx4 v[6:9], v[6:7], off
	v_lshl_add_u64 v[10:11], v[34:35], 0, v[150:151]
	global_load_dwordx4 v[10:13], v[10:11], off
	v_lshl_add_u64 v[14:15], v[80:81], 0, v[150:151]
	global_load_dwordx4 v[14:17], v[14:15], off
	s_waitcnt vmcnt(3)
	ds_write_b128 v201, v[2:5]
	s_waitcnt vmcnt(2)
	ds_write_b128 v202, v[6:9]
	s_waitcnt vmcnt(1)
	ds_write_b128 v203, v[10:13]
	s_waitcnt vmcnt(0)
	ds_write_b128 v204, v[14:17]
	s_waitcnt lgkmcnt(0)
	s_barrier
	ds_read_b32 v41, v179 offset:65152
	s_setprio 1
	ds_read_b128 v[2:5], v205
	ds_read_b128 v[18:21], v205 offset:32
	s_waitcnt lgkmcnt(1)
	v_mfma_f32_32x32x16_bf16 v[2:17], v[2:5], v[112:115], 0
	s_waitcnt lgkmcnt(0)
	v_mfma_f32_32x32x16_bf16 v[2:17], v[18:21], v[116:119], v[2:17]
	ds_read_b128 v[18:21], v205 offset:64
	s_waitcnt lgkmcnt(0)
	v_mfma_f32_32x32x16_bf16 v[2:17], v[18:21], v[120:123], v[2:17]
	ds_read_b128 v[18:21], v205 offset:96
	s_waitcnt lgkmcnt(0)
	v_mfma_f32_32x32x16_bf16 v[2:17], v[18:21], v[124:127], v[2:17]
	ds_read_b128 v[18:21], v205 offset:128
	s_waitcnt lgkmcnt(0)
	v_mfma_f32_32x32x16_bf16 v[2:17], v[18:21], v[128:131], v[2:17]
	ds_read_b128 v[18:21], v205 offset:160
	s_waitcnt lgkmcnt(0)
	v_mfma_f32_32x32x16_bf16 v[2:17], v[18:21], v[132:135], v[2:17]
	ds_read_b128 v[18:21], v205 offset:192
	s_waitcnt lgkmcnt(0)
	v_mfma_f32_32x32x16_bf16 v[2:17], v[18:21], v[136:139], v[2:17]
	ds_read_b128 v[18:21], v205 offset:224
	s_waitcnt lgkmcnt(0)
	v_mfma_f32_32x32x16_bf16 v[2:17], v[18:21], v[140:143], v[2:17]
	s_setprio 0
	s_setprio 1
	ds_read_b128 v[18:21], v205 offset:8704
	ds_read_b128 v[42:45], v205 offset:8736
	s_waitcnt lgkmcnt(1)
	v_mfma_f32_32x32x16_bf16 v[18:33], v[18:21], v[112:115], 0
	s_waitcnt lgkmcnt(0)
	v_mfma_f32_32x32x16_bf16 v[18:33], v[42:45], v[116:119], v[18:33]
	ds_read_b128 v[42:45], v205 offset:8768
	s_waitcnt lgkmcnt(0)
	v_mfma_f32_32x32x16_bf16 v[18:33], v[42:45], v[120:123], v[18:33]
	ds_read_b128 v[42:45], v205 offset:8800
	s_waitcnt lgkmcnt(0)
	v_mfma_f32_32x32x16_bf16 v[18:33], v[42:45], v[124:127], v[18:33]
	ds_read_b128 v[42:45], v205 offset:8832
	s_waitcnt lgkmcnt(0)
	v_mfma_f32_32x32x16_bf16 v[18:33], v[42:45], v[128:131], v[18:33]
	ds_read_b128 v[42:45], v205 offset:8864
	s_waitcnt lgkmcnt(0)
	v_mfma_f32_32x32x16_bf16 v[18:33], v[42:45], v[132:135], v[18:33]
	ds_read_b128 v[42:45], v205 offset:8896
	s_waitcnt lgkmcnt(0)
	v_mfma_f32_32x32x16_bf16 v[18:33], v[42:45], v[136:139], v[18:33]
	ds_read_b128 v[42:45], v205 offset:8928
	s_waitcnt lgkmcnt(0)
	v_mfma_f32_32x32x16_bf16 v[18:33], v[42:45], v[140:143], v[18:33]
	s_setprio 0
	v_add_u32_e32 v42, s29, v198
	v_add_u32_e32 v42, 0x3f0, v42
	v_mov_b32_e32 v43, v41
	s_cbranch_scc1 .LBB0_1476
	v_med3_i32 v43, v42, 0, v219
	v_lshl_add_u32 v43, v43, 2, v179
	ds_read_b32 v43, v43 offset:64640

.Lg3_pre:
	s_mov_b64 vcc, exec
	s_nop 1
	v_readfirstlane_b32 s100, v194
	v_readfirstlane_b32 s101, v195
	v_readfirstlane_b32 s26, v202
	v_readfirstlane_b32 s27, v203
	s_nop 3
	s_sub_u32 s26, s26, 0x100000
	s_subb_u32 s27, s27, 0
	s_nop 1
	v_subrev_u32_e32 v202, s26, v202
	v_add_u32_e32 v202, v202, v178
	v_subrev_u32_e32 v203, s26, v200
	v_add_u32_e32 v203, v203, v178
	v_subrev_u32_e32 v230, s26, v198
	v_add_u32_e32 v230, v230, v178
	v_subrev_u32_e32 v231, s26, v196
	v_add_u32_e32 v231, v231, v178
	v_subrev_u32_e32 v232, s100, v194
	v_add_u32_e32 v232, v232, v178
	v_add_u32_e32 v235, v223, v207
	v_add_u32_e32 v236, v225, v207
	v_add_u32_e32 v237, v227, v207
	v_add_u32_e32 v238, v206, v207
	s_branch .Lg3_head
	.p2align 8

.Lg4_pre:
	s_mov_b64 vcc, exec
	s_nop 1
	v_readfirstlane_b32 s100, v196
	v_readfirstlane_b32 s101, v197
	v_readfirstlane_b32 s22, v204
	v_readfirstlane_b32 s23, v205
	s_nop 3
	s_sub_u32 s22, s22, 0x100000
	s_subb_u32 s23, s23, 0
	s_nop 1
	v_subrev_u32_e32 v204, s22, v204
	v_add_u32_e32 v204, v204, v180
	v_subrev_u32_e32 v205, s22, v202
	v_add_u32_e32 v205, v205, v180
	v_subrev_u32_e32 v232, s22, v200
	v_add_u32_e32 v232, v232, v180
	v_subrev_u32_e32 v233, s22, v198
	v_add_u32_e32 v233, v233, v180
	v_subrev_u32_e32 v234, s100, v196
	v_add_u32_e32 v234, v234, v180
	v_add_u32_e32 v237, v225, v223
	v_add_u32_e32 v238, v227, v223
	v_add_u32_e32 v239, v229, v223
	v_add_u32_e32 v240, v222, v223
	s_branch .Lg4_head
	.p2align 8

.LBB0_2107:
	s_or_b64 exec, exec, s[4:5]
	s_xor_b64 s[4:5], s[14:15], -1
	s_lshl_b32 s14, s17, 6
	s_or_b32 s14, s14, s16
	v_or_b32_e32 v130, s14, v1
	v_mov_b32_e32 v131, v0
	v_lshlrev_b64 v[136:137], 2, v[130:131]
	v_lshl_add_u64 v[140:141], s[6:7], 0, v[136:137]
	v_add_co_u32_e32 v132, vcc, 0x8000, v140
	v_or_b32_e32 v138, 0x1000, v130
	s_nop 0
	v_addc_co_u32_e32 v133, vcc, 0, v141, vcc
	v_mov_b32_e32 v139, v0
	v_add_co_u32_e32 v134, vcc, 0x10000, v140
	v_lshlrev_b64 v[138:139], 2, v[138:139]
	s_nop 0
	v_addc_co_u32_e32 v135, vcc, 0, v141, vcc
	v_lshl_add_u64 v[142:143], s[6:7], 0, v[138:139]
	s_waitcnt lgkmcnt(0)
	s_barrier
	global_load_dword v131, v[140:141], off
	v_lshl_add_u64 v[136:137], s[8:9], 0, v[136:137]
	global_load_dword v133, v[132:133], off
	v_lshl_add_u64 v[138:139], s[8:9], 0, v[138:139]
	global_load_dword v135, v[134:135], off
	s_lshl_b32 s84, s14, 1
	global_load_dword v132, v[142:143], off
	v_add_co_u32_e32 v142, vcc, s67, v140
	global_load_dword v137, v[136:137], off
	s_nop 0
	v_addc_co_u32_e32 v143, vcc, 0, v141, vcc
	v_add_co_u32_e32 v140, vcc, 0x14000, v140
	global_load_dword v130, v[142:143], off
	s_nop 0
	v_addc_co_u32_e32 v141, vcc, 0, v141, vcc
	global_load_dword v134, v[140:141], off
	global_load_dword v136, v[138:139], off
	v_lshl_add_u64 v[138:139], v[178:179], 0, s[84:85]
	s_movk_i32 s17, 0xfbf8
	v_mov_b32_e32 v142, v206
	s_waitcnt vmcnt(0)
	s_movk_i32 s18, 0x7fff
.Lffn_row2:
	v_add_u32_e32 v152, s17, v207
	ds_read2st64_b32 v[154:155], v152 offset1:1
	ds_read2_b32 v[156:157], v152 offset0:129 offset1:193
	v_add_u32_e32 v153, 8, v152
	ds_read2st64_b32 v[158:159], v153 offset0:4 offset1:5
	v_add_u32_e32 v153, 0x60c, v152
	ds_read2st64_b32 v[160:161], v153 offset1:1
	v_add_u32_e32 v162, s31, v142
	v_add_u32_e32 v163, 1, v162
	v_cmp_lt_i32_e64 s[20:21], 1, v142
	v_cmp_gt_i32_e32 vcc, s34, v162
	v_ashrrev_i32_e32 v165, 31, v162
	v_mov_b32_e32 v164, v162
	s_and_b64 s[20:21], s[20:21], vcc
	v_cmp_lt_i32_e64 s[22:23], 0, v142
	v_cmp_gt_i32_e32 vcc, s34, v163
	v_lshlrev_b64 v[164:165], 13, v[164:165]
	v_lshl_add_u64 v[164:165], v[138:139], 0, v[164:165]
	s_and_b64 s[22:23], s[22:23], vcc
	v_add_co_u32_e32 v166, vcc, 0x2000, v164
	s_nop 1
	v_addc_co_u32_e32 v167, vcc, 0, v165, vcc
	s_waitcnt lgkmcnt(0)
	v_mul_f32_e32 v168, v133, v156
	v_mul_f32_e32 v170, v133, v158
	v_mul_f32_e32 v169, v132, v155
	v_mul_f32_e32 v171, v132, v157
	v_fma_f32 v168, v131, v154, v168
	v_fma_f32 v170, v131, v156, v170
	v_fma_f32 v169, v130, v157, v169
	v_fma_f32 v171, v130, v159, v171
	v_fma_f32 v168, v135, v158, v168
	v_fma_f32 v170, v135, v160, v170
	v_fma_f32 v169, v134, v159, v169
	v_fma_f32 v171, v134, v161, v171
	v_add_f32_e32 v168, v137, v168
	v_add_f32_e32 v170, v137, v170
	v_add_f32_e32 v169, v136, v169
	v_add_f32_e32 v171, v136, v171
	v_mul_f32_e32 v172, 0xbfb8aa3b, v168
	v_mul_f32_e32 v173, 0xbfb8aa3b, v170
	v_exp_f32_e32 v172, v172
	v_exp_f32_e32 v173, v173
	s_nop 0
	v_add_f32_e32 v172, 1.0, v172
	v_add_f32_e32 v173, 1.0, v173
	v_rcp_f32_e32 v172, v172
	v_rcp_f32_e32 v173, v173
	s_nop 0
	v_mul_f32_e32 v172, v168, v172
	v_mul_f32_e32 v173, v170, v173
	v_mul_f32_e32 v172, v169, v172
	v_mul_f32_e32 v173, v171, v173
	v_bfe_u32 v174, v172, 16, 1
	v_bfe_u32 v175, v173, 16, 1
	v_add3_u32 v172, v172, v174, s18
	v_add3_u32 v173, v173, v175, s18
	s_mov_b64 s[14:15], exec
	s_and_b64 exec, s[14:15], s[20:21]
	global_store_short_d16_hi v[164:165], v172, off
	s_and_b64 exec, s[14:15], s[22:23]
	global_store_short_d16_hi v[166:167], v173, off
	s_mov_b64 exec, s[14:15]
	s_addk_i32 s17, 0x408
	v_add_u32_e32 v142, 2, v142
	s_cmpk_eq_i32 s17, 0x3c78
	s_cbranch_scc0 .Lffn_row2
	s_branch .LBB0_2104

.Lg5_pre:
	s_mov_b64 vcc, exec
	s_nop 1
	v_readfirstlane_b32 s100, v194
	v_readfirstlane_b32 s101, v195
	v_readfirstlane_b32 s20, v202
	v_readfirstlane_b32 s21, v203
	s_nop 3
	s_sub_u32 s20, s20, 0x100000
	s_subb_u32 s21, s21, 0
	s_nop 1
	v_subrev_u32_e32 v202, s20, v202
	v_add_u32_e32 v202, v202, v178
	v_subrev_u32_e32 v203, s20, v200
	v_add_u32_e32 v203, v203, v178
	v_subrev_u32_e32 v230, s20, v198
	v_add_u32_e32 v230, v230, v178
	v_subrev_u32_e32 v231, s20, v196
	v_add_u32_e32 v231, v231, v178
	v_subrev_u32_e32 v232, s100, v194
	v_add_u32_e32 v232, v232, v178
	v_add_u32_e32 v235, v223, v207
	v_add_u32_e32 v236, v225, v207
	v_add_u32_e32 v237, v227, v207
	v_add_u32_e32 v238, v206, v207
	s_branch .Lg5_head
	.p2align 8
